# residual-epilogue loads of the leading wave half issued before its align barrier (P2,P7,P9)
# speedup vs baseline: 1.0058x; 1.0032x over previous
; __device__ __forceinline__ unsigned cvt_pk_bf16(float lo, float hi) { unsigned r; asm volatile("v_cvt_pk_bf16_f32 %0, %1, %2" : "=v"(r) : "v"(lo), "v"(hi)); return r; }
; #define PG8_BAR __builtin_amdgcn_s_barrier()
;     __device__ __forceinline__ void operator()(const f32x4 (&acc)[2][2][4][2], const Unit& u, int wr, int wc, int fr, int fq) const {
;         const int row0 = u.pm * BM + wr * 64 + fr, col0 = u.pn * BM + wc * 32 + 8 * fq;
; #pragma unroll
;         for (int ai = 0; ai < 2; ++ai) {
;         u32x4 xin[1][4][2];
;         if (XI_BF16) {
; #pragma unroll
;                 for (int m = 0; m < 4; ++m)
; #pragma unroll
;                     for (int bj = 0; bj < 2; ++bj) xin[0][m][bj] = *(const u32x4*)(xb + (size_t)(row0 + ai * HALF + m * 16) * DM + col0 + bj * HALF);
;         }
; #pragma unroll
;             for (int m = 0; m < 4; ++m) {
;                 const int row = row0 + ai * HALF + m * 16; const size_t off = (size_t)row * DM + col0; float q = 0.f;
; #pragma unroll
;                 for (int bj = 0; bj < 2; ++bj) {
;                     const size_t o2 = off + bj * HALF; f32x4 b0, b1;
;                     if (XI_BF16) bf8_to_f32(xin[0][m][bj], b0, b1); else { b0 = *(const f32x4*)(xi + o2); b1 = *(const f32x4*)(xi + o2 + 4); }
;                     const f32x4 o0 = b0 + acc[ai][bj][m][0] * scale, o1 = b1 + acc[ai][bj][m][1] * scale;
;                     u32x4 w; w.x = cvt_pk_bf16(o0[0], o0[1]); w.y = cvt_pk_bf16(o0[2], o0[3]); w.z = cvt_pk_bf16(o1[0], o1[1]); w.w = cvt_pk_bf16(o1[2], o1[3]);
;                     *(u32x4*)(xb + o2) = w;
;                     q += ((o0[0] * o0[0] + o0[1] * o0[1]) + (o0[2] * o0[2] + o0[3] * o0[3])) + ((o1[0] * o1[0] + o1[1] * o1[1]) + (o1[2] * o1[2] + o1[3] * o1[3]));
;                 }
;                 q += __shfl_xor(q, 16); q += __shfl_xor(q, 32);
;                 if (fq == 0) ssout[(size_t)row * 16 + u.pn * 4 + wc] = q;
; template <class Epi, class Sched, bool ALIGN_EPI = false, bool SP2 = false>
; __device__ __forceinline__ void gemm_phase(PG8_LAS unsigned char* lds, const Gemm g, const Sched& S, const Epi& E) {
;     ...
;         if constexpr (ALIGN_EPI) { if (wr == 0) PG8_BAR; }
.Lpeel_done_g1:
.LBB0_375:
	v_lshl_or_b32 v128, s34, 5, v244
	v_lshl_or_b32 v184, s4, 8, v128
	v_lshl_add_u32 v188, s45, 8, v157
	v_ashrrev_i32_e32 v185, 31, v184
	v_lshlrev_b64 v[214:215], 1, v[184:185]
	v_ashrrev_i32_e32 v189, 31, v188
	v_lshl_add_u64 v[186:187], s[76:77], 0, v[214:215]
	v_lshlrev_b64 v[204:205], 11, v[188:189]
	v_lshl_add_u64 v[128:129], v[186:187], 0, v[204:205]
	global_load_dwordx4 v[206:209], v[128:129], off
	global_load_dwordx4 v[210:213], v[128:129], off offset:256
	v_or_b32_e32 v198, 16, v188
	v_or_b32_e32 v194, 32, v188
	v_or_b32_e32 v190, 48, v188
	v_ashrrev_i32_e32 v199, 31, v198
	v_ashrrev_i32_e32 v195, 31, v194
	v_ashrrev_i32_e32 v191, 31, v190
	v_lshlrev_b64 v[200:201], 11, v[198:199]
	v_lshlrev_b64 v[196:197], 11, v[194:195]
	v_lshlrev_b64 v[192:193], 11, v[190:191]
	v_lshl_add_u64 v[128:129], v[186:187], 0, v[200:201]
	v_lshl_add_u64 v[130:131], v[186:187], 0, v[196:197]
	v_lshl_add_u64 v[216:217], v[186:187], 0, v[192:193]
	global_load_dwordx4 v[148:151], v[128:129], off
	global_load_dwordx4 v[144:147], v[128:129], off offset:256
	global_load_dwordx4 v[140:143], v[130:131], off
	global_load_dwordx4 v[136:139], v[130:131], off offset:256
	global_load_dwordx4 v[132:135], v[216:217], off
	s_nop 0
	global_load_dwordx4 v[128:131], v[216:217], off offset:256
	s_cmp_eq_u64 s[16:17], 0
	s_cbranch_scc1 .Lalign_p2
	s_barrier
.Lalign_p2:
	v_and_b32_e32 v217, 64, v203
	v_xor_b32_e32 v216, 16, v203
	v_add_u32_e32 v217, 64, v217
	v_xor_b32_e32 v218, 32, v203
	v_cmp_lt_i32_e32 vcc, v216, v217
	s_lshl_b32 s20, s4, 2
	s_ashr_i32 s21, s20, 31
	v_cndmask_b32_e32 v219, v203, v216, vcc
	v_cmp_lt_i32_e32 vcc, v218, v217
	v_lshl_add_u64 v[216:217], s[76:77], 0, v[204:205]
	v_lshlrev_b32_e32 v204, 2, v219
	v_cndmask_b32_e32 v224, v203, v218, vcc
	v_lshl_add_u64 v[214:215], v[216:217], 0, v[214:215]
	s_waitcnt vmcnt(0)
	v_lshlrev_b32_e32 v216, 16, v206
	v_and_b32_e32 v217, 0xffff0000, v206
	v_lshlrev_b32_e32 v206, 16, v207
	v_and_b32_e32 v207, 0xffff0000, v207
	v_lshlrev_b32_e32 v218, 16, v208
	v_and_b32_e32 v219, 0xffff0000, v208
	v_lshlrev_b32_e32 v208, 16, v209
	v_and_b32_e32 v209, 0xffff0000, v209
	v_lshlrev_b32_e32 v220, 16, v210
	v_and_b32_e32 v221, 0xffff0000, v210
	v_lshlrev_b32_e32 v210, 16, v211
	v_and_b32_e32 v211, 0xffff0000, v211
	v_lshlrev_b32_e32 v222, 16, v212
	v_and_b32_e32 v223, 0xffff0000, v212
	v_lshlrev_b32_e32 v212, 16, v213
	v_and_b32_e32 v213, 0xffff0000, v213
	v_pk_fma_f32 v[126:127], v[126:127], 0.5, v[206:207] op_sel_hi:[1,0,1]
	v_pk_fma_f32 v[124:125], v[124:125], 0.5, v[216:217] op_sel_hi:[1,0,1]
	v_pk_fma_f32 v[122:123], v[122:123], 0.5, v[208:209] op_sel_hi:[1,0,1]
	v_pk_fma_f32 v[120:121], v[120:121], 0.5, v[218:219] op_sel_hi:[1,0,1]
	v_pk_fma_f32 v[118:119], v[118:119], 0.5, v[210:211] op_sel_hi:[1,0,1]
	v_pk_fma_f32 v[116:117], v[116:117], 0.5, v[220:221] op_sel_hi:[1,0,1]
	v_pk_fma_f32 v[206:207], v[114:115], 0.5, v[212:213] op_sel_hi:[1,0,1]
	v_pk_fma_f32 v[208:209], v[112:113], 0.5, v[222:223] op_sel_hi:[1,0,1]
	v_cvt_pk_bf16_f32 v112, v124, v125
	v_cvt_pk_bf16_f32 v113, v126, v127
	v_mul_f32_e32 v114, v125, v125
	v_mul_f32_e32 v115, v127, v127
	v_mul_f32_e32 v125, v121, v121
	v_mul_f32_e32 v127, v123, v123
	v_mul_f32_e32 v205, v117, v117
	v_mul_f32_e32 v210, v119, v119
	v_mul_f32_e32 v211, v209, v209
	v_mul_f32_e32 v212, v207, v207
	v_fmac_f32_e32 v114, v124, v124
	v_fmac_f32_e32 v115, v126, v126
	v_fmac_f32_e32 v125, v120, v120
	v_fmac_f32_e32 v127, v122, v122
	v_fmac_f32_e32 v205, v116, v116
	v_fmac_f32_e32 v210, v118, v118
	v_fmac_f32_e32 v211, v208, v208
	v_fmac_f32_e32 v212, v206, v206
	v_add_f32_e32 v114, v114, v115
	v_add_f32_e32 v115, v125, v127
	v_add_f32_e32 v124, v205, v210
	v_add_f32_e32 v125, v211, v212
	v_add_f32_e32 v114, v114, v115
	v_add_f32_e32 v115, v124, v125
	v_add_f32_e32 v124, v114, v115
	ds_bpermute_b32 v125, v204, v124
	v_cvt_pk_bf16_f32 v114, v120, v121
	v_cvt_pk_bf16_f32 v115, v122, v123
	global_store_dwordx4 v[214:215], v[112:115], off
	v_cvt_pk_bf16_f32 v116, v116, v117
	v_cvt_pk_bf16_f32 v117, v118, v119
	v_cvt_pk_bf16_f32 v118, v208, v209
	v_cvt_pk_bf16_f32 v119, v206, v207
	global_store_dwordx4 v[214:215], v[116:119], off offset:256
	s_waitcnt lgkmcnt(0)
	v_add_f32_e32 v113, v124, v125
	v_lshlrev_b32_e32 v112, 2, v224
	ds_bpermute_b32 v114, v112, v113
	s_and_saveexec_b64 s[24:25], s[8:9]
	s_cbranch_execz .LBB0_377
	v_lshlrev_b64 v[116:117], 6, v[188:189]
	v_lshl_add_u64 v[116:117], s[14:15], 0, v[116:117]
	v_lshl_add_u64 v[116:117], s[20:21], 2, v[116:117]
	s_lshl_b32 s4, s34, 2
	v_lshl_add_u64 v[116:117], v[116:117], 0, s[4:5]
	s_waitcnt lgkmcnt(0)
	v_add_f32_e32 v113, v113, v114
	global_store_dword v[116:117], v113, off

; __device__ __forceinline__ unsigned cvt_pk_bf16(float lo, float hi) { unsigned r; asm volatile("v_cvt_pk_bf16_f32 %0, %1, %2" : "=v"(r) : "v"(lo), "v"(hi)); return r; }
; #define PG8_BAR __builtin_amdgcn_s_barrier()
;     __device__ __forceinline__ void operator()(const f32x4 (&acc)[2][2][4][2], const Unit& u, int wr, int wc, int fr, int fq) const {
;         const int row0 = u.pm * BM + wr * 64 + fr, col0 = u.pn * BM + wc * 32 + 8 * fq;
; #pragma unroll
;         for (int ai = 0; ai < 2; ++ai) {
;         u32x4 xin[1][4][2];
;         if (XI_BF16) {
; #pragma unroll
;                 for (int m = 0; m < 4; ++m)
; #pragma unroll
;                     for (int bj = 0; bj < 2; ++bj) xin[0][m][bj] = *(const u32x4*)(xb + (size_t)(row0 + ai * HALF + m * 16) * DM + col0 + bj * HALF);
;         }
; #pragma unroll
;             for (int m = 0; m < 4; ++m) {
;                 const int row = row0 + ai * HALF + m * 16; const size_t off = (size_t)row * DM + col0; float q = 0.f;
; #pragma unroll
;                 for (int bj = 0; bj < 2; ++bj) {
;                     const size_t o2 = off + bj * HALF; f32x4 b0, b1;
;                     if (XI_BF16) bf8_to_f32(xin[0][m][bj], b0, b1); else { b0 = *(const f32x4*)(xi + o2); b1 = *(const f32x4*)(xi + o2 + 4); }
;                     const f32x4 o0 = b0 + acc[ai][bj][m][0] * scale, o1 = b1 + acc[ai][bj][m][1] * scale;
;                     u32x4 w; w.x = cvt_pk_bf16(o0[0], o0[1]); w.y = cvt_pk_bf16(o0[2], o0[3]); w.z = cvt_pk_bf16(o1[0], o1[1]); w.w = cvt_pk_bf16(o1[2], o1[3]);
;                     *(u32x4*)(xb + o2) = w;
;                     q += ((o0[0] * o0[0] + o0[1] * o0[1]) + (o0[2] * o0[2] + o0[3] * o0[3])) + ((o1[0] * o1[0] + o1[1] * o1[1]) + (o1[2] * o1[2] + o1[3] * o1[3]));
;                 }
;                 q += __shfl_xor(q, 16); q += __shfl_xor(q, 32);
;                 if (fq == 0) ssout[(size_t)row * 16 + u.pn * 4 + wc] = q;
; template <class Epi, class Sched, bool ALIGN_EPI = false, bool SP2 = false>
; __device__ __forceinline__ void gemm_phase(PG8_LAS unsigned char* lds, const Gemm g, const Sched& S, const Epi& E) {
;     ...
;         if constexpr (ALIGN_EPI) { if (wr == 0) PG8_BAR; }
.Lpeel_done_g3:
.LBB0_1233:
	v_lshl_or_b32 v182, s0, 8, v171
	v_lshl_add_u32 v186, s24, 8, v165
	v_ashrrev_i32_e32 v183, 31, v182
	v_lshlrev_b64 v[214:215], 1, v[182:183]
	v_ashrrev_i32_e32 v187, 31, v186
	v_lshl_add_u64 v[184:185], s[76:77], 0, v[214:215]
	v_lshlrev_b64 v[204:205], 11, v[186:187]
	v_lshl_add_u64 v[128:129], v[184:185], 0, v[204:205]
	global_load_dwordx4 v[206:209], v[128:129], off
	global_load_dwordx4 v[210:213], v[128:129], off offset:256
	v_or_b32_e32 v196, 16, v186
	v_or_b32_e32 v192, 32, v186
	v_or_b32_e32 v188, 48, v186
	v_ashrrev_i32_e32 v197, 31, v196
	v_ashrrev_i32_e32 v193, 31, v192
	v_ashrrev_i32_e32 v189, 31, v188
	v_lshlrev_b64 v[198:199], 11, v[196:197]
	v_lshlrev_b64 v[194:195], 11, v[192:193]
	v_lshlrev_b64 v[190:191], 11, v[188:189]
	v_lshl_add_u64 v[128:129], v[184:185], 0, v[198:199]
	v_lshl_add_u64 v[130:131], v[184:185], 0, v[194:195]
	v_lshl_add_u64 v[216:217], v[184:185], 0, v[190:191]
	global_load_dwordx4 v[148:151], v[128:129], off
	global_load_dwordx4 v[144:147], v[128:129], off offset:256
	global_load_dwordx4 v[140:143], v[130:131], off
	global_load_dwordx4 v[136:139], v[130:131], off offset:256
	global_load_dwordx4 v[132:135], v[216:217], off
	s_nop 0
	global_load_dwordx4 v[128:131], v[216:217], off offset:256
	s_cmp_eq_u64 s[14:15], 0
	s_cbranch_scc1 .Lalign_p7
	s_barrier
.Lalign_p7:
	v_and_b32_e32 v217, 64, v203
	v_xor_b32_e32 v216, 16, v203
	v_add_u32_e32 v217, 64, v217
	v_xor_b32_e32 v218, 32, v203
	v_cmp_lt_i32_e32 vcc, v216, v217
	s_lshl_b32 s24, s0, 2
	s_ashr_i32 s25, s24, 31
	v_cndmask_b32_e32 v219, v203, v216, vcc
	v_cmp_lt_i32_e32 vcc, v218, v217
	v_lshl_add_u64 v[216:217], s[76:77], 0, v[204:205]
	v_lshlrev_b32_e32 v204, 2, v219
	v_cndmask_b32_e32 v224, v203, v218, vcc
	v_lshl_add_u64 v[214:215], v[216:217], 0, v[214:215]
	s_waitcnt vmcnt(0)
	v_lshlrev_b32_e32 v216, 16, v206
	v_and_b32_e32 v217, 0xffff0000, v206
	v_lshlrev_b32_e32 v206, 16, v207
	v_and_b32_e32 v207, 0xffff0000, v207
	v_lshlrev_b32_e32 v218, 16, v208
	v_and_b32_e32 v219, 0xffff0000, v208
	v_lshlrev_b32_e32 v208, 16, v209
	v_and_b32_e32 v209, 0xffff0000, v209
	v_lshlrev_b32_e32 v220, 16, v210
	v_and_b32_e32 v221, 0xffff0000, v210
	v_lshlrev_b32_e32 v210, 16, v211
	v_and_b32_e32 v211, 0xffff0000, v211
	v_lshlrev_b32_e32 v222, 16, v212
	v_and_b32_e32 v223, 0xffff0000, v212
	v_lshlrev_b32_e32 v212, 16, v213
	v_and_b32_e32 v213, 0xffff0000, v213
	v_pk_add_f32 v[126:127], v[126:127], v[206:207]
	v_pk_add_f32 v[124:125], v[124:125], v[216:217]
	v_pk_add_f32 v[122:123], v[122:123], v[208:209]
	v_pk_add_f32 v[120:121], v[120:121], v[218:219]
	v_pk_add_f32 v[118:119], v[118:119], v[210:211]
	v_pk_add_f32 v[116:117], v[116:117], v[220:221]
	v_pk_add_f32 v[206:207], v[114:115], v[212:213]
	v_pk_add_f32 v[208:209], v[112:113], v[222:223]
	v_cvt_pk_bf16_f32 v112, v124, v125
	v_cvt_pk_bf16_f32 v113, v126, v127
	v_mul_f32_e32 v114, v125, v125
	v_mul_f32_e32 v115, v127, v127
	v_mul_f32_e32 v125, v121, v121
	v_mul_f32_e32 v127, v123, v123
	v_mul_f32_e32 v205, v117, v117
	v_mul_f32_e32 v210, v119, v119
	v_mul_f32_e32 v211, v209, v209
	v_mul_f32_e32 v212, v207, v207
	v_fmac_f32_e32 v114, v124, v124
	v_fmac_f32_e32 v115, v126, v126
	v_fmac_f32_e32 v125, v120, v120
	v_fmac_f32_e32 v127, v122, v122
	v_fmac_f32_e32 v205, v116, v116
	v_fmac_f32_e32 v210, v118, v118
	v_fmac_f32_e32 v211, v208, v208
	v_fmac_f32_e32 v212, v206, v206
	v_add_f32_e32 v114, v114, v115
	v_add_f32_e32 v115, v125, v127
	v_add_f32_e32 v124, v205, v210
	v_add_f32_e32 v125, v211, v212
	v_add_f32_e32 v114, v114, v115
	v_add_f32_e32 v115, v124, v125
	v_add_f32_e32 v124, v114, v115
	ds_bpermute_b32 v125, v204, v124
	v_cvt_pk_bf16_f32 v114, v120, v121
	v_cvt_pk_bf16_f32 v115, v122, v123
	global_store_dwordx4 v[214:215], v[112:115], off
	v_cvt_pk_bf16_f32 v116, v116, v117
	v_cvt_pk_bf16_f32 v117, v118, v119
	v_cvt_pk_bf16_f32 v118, v208, v209
	v_cvt_pk_bf16_f32 v119, v206, v207
	global_store_dwordx4 v[214:215], v[116:119], off offset:256
	s_waitcnt lgkmcnt(0)
	v_add_f32_e32 v113, v124, v125
	v_lshlrev_b32_e32 v112, 2, v224
	ds_bpermute_b32 v114, v112, v113
	s_and_saveexec_b64 s[26:27], s[8:9]
	s_cbranch_execz .LBB0_1235
	v_lshlrev_b64 v[116:117], 6, v[186:187]
	v_lshl_add_u64 v[116:117], s[12:13], 0, v[116:117]
	v_lshl_add_u64 v[116:117], s[24:25], 2, v[116:117]
	s_lshl_b32 s0, s38, 2
	v_lshl_add_u64 v[116:117], v[116:117], 0, s[0:1]
	s_waitcnt lgkmcnt(0)
	v_add_f32_e32 v113, v113, v114
	global_store_dword v[116:117], v113, off

; #define PG8_BAR __builtin_amdgcn_s_barrier()
;     __device__ __forceinline__ void operator()(f32x4 (&acc)[2][2][4][2], const Unit& u, int wr, int wc, int fr, int fq) const {
;         const int row0 = u.pm * BM + wr * 64 + fr, col0 = u.pn * BM + wc * 32 + 8 * fq;
; #pragma unroll
;         for (int ai = 0; ai < 2; ++ai) {
;         u32x4 xin[4][2];
; #pragma unroll
;             for (int m = 0; m < 4; ++m)
; #pragma unroll
;                 for (int bj = 0; bj < 2; ++bj) xin[m][bj] = *(const u32x4*)(xb + (size_t)(row0 + ai * HALF + m * 16) * DM + col0 + bj * HALF);
; #pragma unroll
;             for (int m = 0; m < 4; ++m) {
;                 const int row = row0 + ai * HALF + m * 16; float q = 0.f;
; #pragma unroll
;                 for (int bj = 0; bj < 2; ++bj) {
;                     f32x4 b0, b1; bf8_to_f32(xin[m][bj], b0, b1);
;                     const f32x4 o0 = b0 + acc[ai][bj][m][0] * scale, o1 = b1 + acc[ai][bj][m][1] * scale;
;                     acc[ai][bj][m][0] = o0; acc[ai][bj][m][1] = o1;
;                     q += ((o0[0] * o0[0] + o0[1] * o0[1]) + (o0[2] * o0[2] + o0[3] * o0[3])) + ((o1[0] * o1[0] + o1[1] * o1[1]) + (o1[2] * o1[2] + o1[3] * o1[3]));
;                 }
;                 q += __shfl_xor(q, 16); q += __shfl_xor(q, 32);
;                 if (fq == 0) __hip_atomic_store((unsigned*)(ss + (size_t)row * 16 + u.pn * 4 + wc), __float_as_uint(q), __ATOMIC_RELAXED, __HIP_MEMORY_SCOPE_AGENT);
; template <class Epi, class Sched, bool ALIGN_EPI = false, bool SP2 = false>
; __device__ __forceinline__ void gemm_phase(PG8_LAS unsigned char* lds, const Gemm g, const Sched& S, const Epi& E) {
;     ...
;         if constexpr (ALIGN_EPI) { if (wr == 0) PG8_BAR; }
.Lpeel_done_g5:
.LBB0_1445:
	v_lshl_add_u32 v176, s47, 8, v210
	v_lshl_or_b32 v190, s12, 8, v212
	v_ashrrev_i32_e32 v191, 31, v190
	v_ashrrev_i32_e32 v177, 31, v176
	v_lshl_add_u64 v[192:193], v[190:191], 1, s[76:77]
	v_lshlrev_b64 v[128:129], 11, v[176:177]
	v_lshl_add_u64 v[128:129], v[192:193], 0, v[128:129]
	global_load_dwordx4 v[178:181], v[128:129], off
	global_load_dwordx4 v[182:185], v[128:129], off offset:256
	v_or_b32_e32 v174, 16, v176
	v_or_b32_e32 v172, 32, v176
	v_or_b32_e32 v162, 48, v176
	v_ashrrev_i32_e32 v175, 31, v174
	v_ashrrev_i32_e32 v173, 31, v172
	v_ashrrev_i32_e32 v163, 31, v162
	v_lshlrev_b64 v[128:129], 11, v[174:175]
	v_lshlrev_b64 v[130:131], 11, v[172:173]
	v_lshlrev_b64 v[132:133], 11, v[162:163]
	v_lshl_add_u64 v[128:129], v[192:193], 0, v[128:129]
	v_lshl_add_u64 v[130:131], v[192:193], 0, v[130:131]
	v_lshl_add_u64 v[186:187], v[192:193], 0, v[132:133]
	global_load_dwordx4 v[148:151], v[128:129], off
	global_load_dwordx4 v[144:147], v[128:129], off offset:256
	global_load_dwordx4 v[140:143], v[130:131], off
	global_load_dwordx4 v[136:139], v[130:131], off offset:256
	global_load_dwordx4 v[132:135], v[186:187], off
	s_nop 0
	global_load_dwordx4 v[128:131], v[186:187], off offset:256
	s_cmp_eq_u64 s[20:21], 0
	s_cbranch_scc1 .Lalign_p9
	s_barrier
.Lalign_p9:
	v_and_b32_e32 v187, 64, v216
	v_xor_b32_e32 v186, 16, v216
	v_add_u32_e32 v198, 64, v187
	v_cmp_lt_i32_e32 vcc, v186, v198
	s_lshl_b32 s6, s12, 2
	s_ashr_i32 s7, s6, 31
	v_cndmask_b32_e32 v186, v216, v186, vcc
	v_lshlrev_b32_e32 v219, 2, v186
	v_lshlrev_b64 v[200:201], 6, v[176:177]
	s_waitcnt vmcnt(0)
	v_lshlrev_b32_e32 v186, 16, v178
	v_and_b32_e32 v187, 0xffff0000, v178
	v_lshlrev_b32_e32 v178, 16, v179
	v_and_b32_e32 v179, 0xffff0000, v179
	v_lshlrev_b32_e32 v188, 16, v180
	v_and_b32_e32 v189, 0xffff0000, v180
	v_lshlrev_b32_e32 v180, 16, v181
	v_and_b32_e32 v181, 0xffff0000, v181
	v_lshlrev_b32_e32 v194, 16, v182
	v_and_b32_e32 v195, 0xffff0000, v182
	v_lshlrev_b32_e32 v182, 16, v183
	v_and_b32_e32 v183, 0xffff0000, v183
	v_lshlrev_b32_e32 v196, 16, v184
	v_and_b32_e32 v197, 0xffff0000, v184
	v_lshlrev_b32_e32 v184, 16, v185
	v_and_b32_e32 v185, 0xffff0000, v185
	v_pk_fma_f32 v[126:127], v[126:127], 0.5, v[178:179] op_sel_hi:[1,0,1]
	v_pk_fma_f32 v[124:125], v[124:125], 0.5, v[186:187] op_sel_hi:[1,0,1]
	v_pk_fma_f32 v[122:123], v[122:123], 0.5, v[180:181] op_sel_hi:[1,0,1]
	v_pk_fma_f32 v[120:121], v[120:121], 0.5, v[188:189] op_sel_hi:[1,0,1]
	v_pk_fma_f32 v[118:119], v[118:119], 0.5, v[182:183] op_sel_hi:[1,0,1]
	v_pk_fma_f32 v[116:117], v[116:117], 0.5, v[194:195] op_sel_hi:[1,0,1]
	v_pk_fma_f32 v[114:115], v[114:115], 0.5, v[184:185] op_sel_hi:[1,0,1]
	v_pk_fma_f32 v[112:113], v[112:113], 0.5, v[196:197] op_sel_hi:[1,0,1]
	v_mul_f32_e32 v178, v125, v125
	v_mul_f32_e32 v179, v127, v127
	v_mul_f32_e32 v180, v121, v121
	v_mul_f32_e32 v181, v123, v123
	v_mul_f32_e32 v182, v117, v117
	v_mul_f32_e32 v183, v119, v119
	v_mul_f32_e32 v184, v113, v113
	v_mul_f32_e32 v185, v115, v115
	v_fmac_f32_e32 v178, v124, v124
	v_fmac_f32_e32 v179, v126, v126
	v_fmac_f32_e32 v180, v120, v120
	v_fmac_f32_e32 v181, v122, v122
	v_fmac_f32_e32 v182, v116, v116
	v_fmac_f32_e32 v183, v118, v118
	v_fmac_f32_e32 v184, v112, v112
	v_fmac_f32_e32 v185, v114, v114
	v_add_f32_e32 v178, v178, v179
	v_add_f32_e32 v179, v180, v181
	v_add_f32_e32 v180, v182, v183
	v_add_f32_e32 v181, v184, v185
	v_add_f32_e32 v178, v178, v179
	v_add_f32_e32 v179, v180, v181
	v_add_f32_e32 v178, v178, v179
	ds_bpermute_b32 v179, v219, v178
	v_xor_b32_e32 v180, 32, v216
	v_cmp_lt_i32_e32 vcc, v180, v198
	s_waitcnt lgkmcnt(0)
	v_add_f32_e32 v178, v178, v179
	v_cndmask_b32_e32 v180, v216, v180, vcc
	v_lshlrev_b32_e32 v220, 2, v180
	ds_bpermute_b32 v179, v220, v178
	s_and_saveexec_b64 s[10:11], s[0:1]
	s_cbranch_execz .LBB0_1447
	s_waitcnt lgkmcnt(0)
	v_add_f32_e32 v180, v178, v179
	v_lshl_add_u64 v[178:179], s[16:17], 0, v[200:201]
	v_lshl_add_u64 v[178:179], s[6:7], 2, v[178:179]
	s_lshl_b32 s12, s36, 2
	v_lshl_add_u64 v[178:179], v[178:179], 0, s[12:13]
	global_store_dword v[178:179], v180, off sc1
